# nt cache policy on the once-read, fully coalesced q/k input loads of fox_prep (on top of nt on the scan pass-3 chunk-image DMA)
# baseline (speedup 1.0000x reference)
; __device__ __forceinline__ float bflo(unsigned u) { return __uint_as_float(u << 16); }
; __device__ __forceinline__ float bfhi(unsigned u) { return __uint_as_float(u & 0xffff0000u); }
; DI float bflo(unsigned u) { return __uint_as_float(u << 16); }
; DI float bfhi(unsigned u) { return __uint_as_float(u & 0xffff0000u); }
; DI void fox_prep_unit(const Params& P, int n, unsigned char* lds, int tid) {
;     ...
;     bf16_t* FQ = (bf16_t*)(ws + WS_PROJ) + 4 * BUF_ELEMS + (size_t)tok * 512 + h * 64;
;     bf16_t* FK = (bf16_t*)(ws + WS_PROJ) + 5 * BUF_ELEMS + (size_t)tok * 512 + h * 64;
;     const bf16_t* FV = (const bf16_t*)(ws + WS_PROJ) + 6 * BUF_ELEMS + (size_t)tok * 512 + h * 64;
; #pragma unroll
;     for (int which = 0; which < 2; ++which) {
;         bf16_t* ptr = which ? FK : FQ; const float* nw = which ? P.in[10] : P.in[9]; const float sc = which ? 1.0f : 0.125f * 1.4426950408889634f;
;         u32x4 raw[8]; float ss = 0.f;
; #pragma unroll
;         for (int i = 0; i < 8; ++i) { raw[i] = *(const u32x4*)(ptr + 8 * i);
;             const float a0 = bflo(raw[i].x), a1 = bfhi(raw[i].x), a2 = bflo(raw[i].y), a3 = bfhi(raw[i].y), a4 = bflo(raw[i].z), a5 = bfhi(raw[i].z), a6 = bflo(raw[i].w), a7 = bfhi(raw[i].w);
;             ss += (a0 * a0 + a1 * a1) + (a2 * a2 + a3 * a3) + (a4 * a4 + a5 * a5) + (a6 * a6 + a7 * a7); }
;         const float rstd = rsqrtf(ss * (1.f / 64.f) + EPS) * sc;
.LBB0_591:
	v_ashrrev_i32_e32 v27, 31, v26
	v_lshlrev_b64 v[30:31], 10, v[26:27]
	v_add_co_u32_e32 v78, vcc, s17, v28
	s_nop 1
	v_addc_co_u32_e32 v79, vcc, 0, v29, vcc
	v_add_co_u32_e32 v80, vcc, s18, v28
	s_nop 1
	v_addc_co_u32_e32 v81, vcc, 0, v29, vcc
	v_add_co_u32_e32 v82, vcc, s19, v28
	v_lshl_add_u64 v[74:75], v[18:19], 0, v[30:31]
	s_nop 1
	v_addc_co_u32_e32 v83, vcc, 0, v29, vcc
	v_add_co_u32_e32 v84, vcc, s20, v28
	s_nop 1
	v_addc_co_u32_e32 v85, vcc, 0, v29, vcc
	v_add_co_u32_e32 v86, vcc, s21, v28
	s_nop 1
	v_addc_co_u32_e32 v87, vcc, 0, v29, vcc
	global_load_dwordx4 v[30:33], v[74:75], off
	global_load_dwordx4 v[40:43], v[74:75], off offset:16
	global_load_dwordx4 v[54:57], v[74:75], off offset:32
	global_load_dwordx4 v[58:61], v[74:75], off offset:48
	global_load_dwordx4 v[62:65], v[74:75], off offset:64
	global_load_dwordx4 v[66:69], v[74:75], off offset:80
	global_load_dwordx4 v[70:73], v[74:75], off offset:96
	global_load_dwordx4 v[74:77], v[74:75], off offset:112
	v_readlane_b32 s36, v239, 3
	v_readlane_b32 s37, v239, 4
	v_readlane_b32 s40, v239, 14
	v_readlane_b32 s41, v239, 15
	v_readlane_b32 s42, v239, 16
	v_readlane_b32 s43, v239, 17
	s_lshl_b32 s28, s27, 16
	s_add_u32 s36, s36, s28
	s_addc_u32 s37, s37, 0
	s_add_u32 s38, s36, 0x8500000
	s_addc_u32 s39, s37, 0
	s_add_u32 s36, s36, 0x7500000
	s_addc_u32 s37, s37, 0
	s_mov_b64 s[44:45], s[36:37]
	s_mov_b64 s[46:47], s[38:39]
	v_lshlrev_b32_e32 v2, 4, v162
	v_and_b32_e32 v3, 7, v162
	v_lshlrev_b32_e32 v3, 5, v3
	s_nop 1
	global_load_dwordx4 v[240:243], v3, s[40:41]
	global_load_dwordx4 v[244:247], v3, s[40:41] offset:16
	global_load_dwordx4 v[110:113], v2, s[36:37] nt
	s_add_u32 s36, s36, 0x2000
	s_addc_u32 s37, s37, 0
	global_load_dwordx4 v[114:117], v2, s[36:37] nt
	s_add_u32 s36, s36, 0x2000
	s_addc_u32 s37, s37, 0
	global_load_dwordx4 v[118:121], v2, s[36:37] nt
	s_add_u32 s36, s36, 0x2000
	s_addc_u32 s37, s37, 0
	global_load_dwordx4 v[122:125], v2, s[36:37] nt
	s_add_u32 s36, s36, 0x2000
	s_addc_u32 s37, s37, 0
	global_load_dwordx4 v[126:129], v2, s[36:37] nt
	s_add_u32 s36, s36, 0x2000
	s_addc_u32 s37, s37, 0
	global_load_dwordx4 v[130:133], v2, s[36:37] nt
	s_add_u32 s36, s36, 0x2000
	s_addc_u32 s37, s37, 0
	global_load_dwordx4 v[134:137], v2, s[36:37] nt
	s_add_u32 s36, s36, 0x2000
	s_addc_u32 s37, s37, 0
	global_load_dwordx4 v[138:141], v2, s[36:37] nt
	global_load_dwordx4 v[88:91], v2, s[38:39] nt
	s_add_u32 s38, s38, 0x2000
	s_addc_u32 s39, s39, 0
	global_load_dwordx4 v[92:95], v2, s[38:39] nt
	s_add_u32 s38, s38, 0x2000
	s_addc_u32 s39, s39, 0
	global_load_dwordx4 v[96:99], v2, s[38:39] nt
	s_add_u32 s38, s38, 0x2000
	s_addc_u32 s39, s39, 0
	global_load_dwordx4 v[100:103], v2, s[38:39] nt
	s_add_u32 s38, s38, 0x2000
	s_addc_u32 s39, s39, 0
	global_load_dwordx4 v[44:47], v2, s[38:39] nt
	s_add_u32 s38, s38, 0x2000
	s_addc_u32 s39, s39, 0
	global_load_dwordx4 v[48:51], v2, s[38:39] nt
	s_add_u32 s38, s38, 0x2000
	s_addc_u32 s39, s39, 0
	global_load_dwordx4 v[4:7], v2, s[38:39] nt
	s_add_u32 s38, s38, 0x2000
	s_addc_u32 s39, s39, 0
	global_load_dwordx4 v[8:11], v2, s[38:39] nt
	s_waitcnt vmcnt(15)
	v_lshlrev_b32_e32 v34, 16, v110
	v_and_b32_e32 v35, 0xffff0000, v110
	v_lshlrev_b32_e32 v36, 16, v111
	v_and_b32_e32 v37, 0xffff0000, v111
	v_lshlrev_b32_e32 v38, 16, v112
	v_and_b32_e32 v39, 0xffff0000, v112
	v_lshlrev_b32_e32 v52, 16, v113
	v_and_b32_e32 v53, 0xffff0000, v113
	v_mul_f32_e32 v248, v34, v34
	v_fmac_f32_e32 v248, v35, v35
	v_fmac_f32_e32 v248, v36, v36
	v_fmac_f32_e32 v248, v37, v37
	v_fmac_f32_e32 v248, v38, v38
	v_fmac_f32_e32 v248, v39, v39
	v_fmac_f32_e32 v248, v52, v52
	v_fmac_f32_e32 v248, v53, v53
	s_waitcnt vmcnt(14)
	v_lshlrev_b32_e32 v34, 16, v114
	v_and_b32_e32 v35, 0xffff0000, v114
	v_lshlrev_b32_e32 v36, 16, v115
	v_and_b32_e32 v37, 0xffff0000, v115
	v_lshlrev_b32_e32 v38, 16, v116
	v_and_b32_e32 v39, 0xffff0000, v116
	v_lshlrev_b32_e32 v52, 16, v117
	v_and_b32_e32 v53, 0xffff0000, v117
	v_mul_f32_e32 v249, v34, v34
	v_fmac_f32_e32 v249, v35, v35
	v_fmac_f32_e32 v249, v36, v36
	v_fmac_f32_e32 v249, v37, v37
	v_fmac_f32_e32 v249, v38, v38
	v_fmac_f32_e32 v249, v39, v39
	v_fmac_f32_e32 v249, v52, v52
	v_fmac_f32_e32 v249, v53, v53
	s_waitcnt vmcnt(13)
	v_lshlrev_b32_e32 v34, 16, v118
	v_and_b32_e32 v35, 0xffff0000, v118
	v_lshlrev_b32_e32 v36, 16, v119
	v_and_b32_e32 v37, 0xffff0000, v119
	v_lshlrev_b32_e32 v38, 16, v120
	v_and_b32_e32 v39, 0xffff0000, v120
	v_lshlrev_b32_e32 v52, 16, v121
	v_and_b32_e32 v53, 0xffff0000, v121
	v_mul_f32_e32 v250, v34, v34
	v_fmac_f32_e32 v250, v35, v35
	v_fmac_f32_e32 v250, v36, v36
	v_fmac_f32_e32 v250, v37, v37
	v_fmac_f32_e32 v250, v38, v38
	v_fmac_f32_e32 v250, v39, v39
	v_fmac_f32_e32 v250, v52, v52
	v_fmac_f32_e32 v250, v53, v53
	s_waitcnt vmcnt(12)
	v_lshlrev_b32_e32 v34, 16, v122
	v_and_b32_e32 v35, 0xffff0000, v122
	v_lshlrev_b32_e32 v36, 16, v123
	v_and_b32_e32 v37, 0xffff0000, v123
	v_lshlrev_b32_e32 v38, 16, v124
	v_and_b32_e32 v39, 0xffff0000, v124
	v_lshlrev_b32_e32 v52, 16, v125
	v_and_b32_e32 v53, 0xffff0000, v125
	v_mul_f32_e32 v251, v34, v34
	v_fmac_f32_e32 v251, v35, v35
	v_fmac_f32_e32 v251, v36, v36
	v_fmac_f32_e32 v251, v37, v37
	v_fmac_f32_e32 v251, v38, v38
	v_fmac_f32_e32 v251, v39, v39
	v_fmac_f32_e32 v251, v52, v52
	v_fmac_f32_e32 v251, v53, v53
	s_waitcnt vmcnt(11)
	v_lshlrev_b32_e32 v34, 16, v126
	v_and_b32_e32 v35, 0xffff0000, v126
	v_lshlrev_b32_e32 v36, 16, v127
	v_and_b32_e32 v37, 0xffff0000, v127
	v_lshlrev_b32_e32 v38, 16, v128
	v_and_b32_e32 v39, 0xffff0000, v128
	v_lshlrev_b32_e32 v52, 16, v129
	v_and_b32_e32 v53, 0xffff0000, v129
	v_mul_f32_e32 v252, v34, v34
	v_fmac_f32_e32 v252, v35, v35
	v_fmac_f32_e32 v252, v36, v36
	v_fmac_f32_e32 v252, v37, v37
	v_fmac_f32_e32 v252, v38, v38
	v_fmac_f32_e32 v252, v39, v39
	v_fmac_f32_e32 v252, v52, v52
	v_fmac_f32_e32 v252, v53, v53
	s_waitcnt vmcnt(10)
; __device__ __forceinline__ float bflo(unsigned u) { return __uint_as_float(u << 16); }
; __device__ __forceinline__ float bfhi(unsigned u) { return __uint_as_float(u & 0xffff0000u); }
; DI float bflo(unsigned u) { return __uint_as_float(u << 16); }
; DI float bfhi(unsigned u) { return __uint_as_float(u & 0xffff0000u); }
; DI unsigned pk2(float lo, float hi) { f32x2_t v = {lo, hi}; bf16x2_t b = __builtin_convertvector(v, bf16x2_t); return __builtin_bit_cast(unsigned, b); }
; DI void fox_prep_unit(const Params& P, int n, unsigned char* lds, int tid) {
;     ...
;             const float a0 = bflo(raw[i].x), a1 = bfhi(raw[i].x), a2 = bflo(raw[i].y), a3 = bfhi(raw[i].y), a4 = bflo(raw[i].z), a5 = bfhi(raw[i].z), a6 = bflo(raw[i].w), a7 = bfhi(raw[i].w);
;             ss += (a0 * a0 + a1 * a1) + (a2 * a2 + a3 * a3) + (a4 * a4 + a5 * a5) + (a6 * a6 + a7 * a7); }
;         const float rstd = rsqrtf(ss * (1.f / 64.f) + EPS) * sc;
; #pragma unroll
;         for (int i = 0; i < 8; ++i) { const f32x4 w0 = *(const f32x4*)(nw + 8 * i), w1 = *(const f32x4*)(nw + 8 * i + 4); u32x4 o;
;             o.x = pk2(bflo(raw[i].x) * rstd * w0.x, bfhi(raw[i].x) * rstd * w0.y); o.y = pk2(bflo(raw[i].y) * rstd * w0.z, bfhi(raw[i].y) * rstd * w0.w);
;             o.z = pk2(bflo(raw[i].z) * rstd * w1.x, bfhi(raw[i].z) * rstd * w1.y); o.w = pk2(bflo(raw[i].w) * rstd * w1.z, bfhi(raw[i].w) * rstd * w1.w);
;             *(u32x4*)(ptr + 8 * i) = o; }
	v_lshlrev_b32_e32 v34, 16, v130
	v_and_b32_e32 v35, 0xffff0000, v130
	v_lshlrev_b32_e32 v36, 16, v131
	v_and_b32_e32 v37, 0xffff0000, v131
	v_lshlrev_b32_e32 v38, 16, v132
	v_and_b32_e32 v39, 0xffff0000, v132
	v_lshlrev_b32_e32 v52, 16, v133
	v_and_b32_e32 v53, 0xffff0000, v133
	v_mul_f32_e32 v253, v34, v34
	v_fmac_f32_e32 v253, v35, v35
	v_fmac_f32_e32 v253, v36, v36
	v_fmac_f32_e32 v253, v37, v37
	v_fmac_f32_e32 v253, v38, v38
	v_fmac_f32_e32 v253, v39, v39
	v_fmac_f32_e32 v253, v52, v52
	v_fmac_f32_e32 v253, v53, v53
	s_waitcnt vmcnt(9)
	v_lshlrev_b32_e32 v34, 16, v134
	v_and_b32_e32 v35, 0xffff0000, v134
	v_lshlrev_b32_e32 v36, 16, v135
	v_and_b32_e32 v37, 0xffff0000, v135
	v_lshlrev_b32_e32 v38, 16, v136
	v_and_b32_e32 v39, 0xffff0000, v136
	v_lshlrev_b32_e32 v52, 16, v137
	v_and_b32_e32 v53, 0xffff0000, v137
	v_mul_f32_e32 v254, v34, v34
	v_fmac_f32_e32 v254, v35, v35
	v_fmac_f32_e32 v254, v36, v36
	v_fmac_f32_e32 v254, v37, v37
	v_fmac_f32_e32 v254, v38, v38
	v_fmac_f32_e32 v254, v39, v39
	v_fmac_f32_e32 v254, v52, v52
	v_fmac_f32_e32 v254, v53, v53
	s_waitcnt vmcnt(8)
	v_lshlrev_b32_e32 v34, 16, v138
	v_and_b32_e32 v35, 0xffff0000, v138
	v_lshlrev_b32_e32 v36, 16, v139
	v_and_b32_e32 v37, 0xffff0000, v139
	v_lshlrev_b32_e32 v38, 16, v140
	v_and_b32_e32 v39, 0xffff0000, v140
	v_lshlrev_b32_e32 v52, 16, v141
	v_and_b32_e32 v53, 0xffff0000, v141
	v_mul_f32_e32 v255, v34, v34
	v_fmac_f32_e32 v255, v35, v35
	v_fmac_f32_e32 v255, v36, v36
	v_fmac_f32_e32 v255, v37, v37
	v_fmac_f32_e32 v255, v38, v38
	v_fmac_f32_e32 v255, v39, v39
	v_fmac_f32_e32 v255, v52, v52
	v_fmac_f32_e32 v255, v53, v53
	v_add_f32_dpp v248, v248, v248 quad_perm:[1,0,3,2] row_mask:0xf bank_mask:0xf bound_ctrl:1
	v_add_f32_dpp v249, v249, v249 quad_perm:[1,0,3,2] row_mask:0xf bank_mask:0xf bound_ctrl:1
	v_add_f32_dpp v250, v250, v250 quad_perm:[1,0,3,2] row_mask:0xf bank_mask:0xf bound_ctrl:1
	v_add_f32_dpp v251, v251, v251 quad_perm:[1,0,3,2] row_mask:0xf bank_mask:0xf bound_ctrl:1
	v_add_f32_dpp v252, v252, v252 quad_perm:[1,0,3,2] row_mask:0xf bank_mask:0xf bound_ctrl:1
	v_add_f32_dpp v253, v253, v253 quad_perm:[1,0,3,2] row_mask:0xf bank_mask:0xf bound_ctrl:1
	v_add_f32_dpp v254, v254, v254 quad_perm:[1,0,3,2] row_mask:0xf bank_mask:0xf bound_ctrl:1
	v_add_f32_dpp v255, v255, v255 quad_perm:[1,0,3,2] row_mask:0xf bank_mask:0xf bound_ctrl:1
	v_add_f32_dpp v248, v248, v248 quad_perm:[2,3,0,1] row_mask:0xf bank_mask:0xf bound_ctrl:1
	v_add_f32_dpp v249, v249, v249 quad_perm:[2,3,0,1] row_mask:0xf bank_mask:0xf bound_ctrl:1
	v_add_f32_dpp v250, v250, v250 quad_perm:[2,3,0,1] row_mask:0xf bank_mask:0xf bound_ctrl:1
	v_add_f32_dpp v251, v251, v251 quad_perm:[2,3,0,1] row_mask:0xf bank_mask:0xf bound_ctrl:1
	v_add_f32_dpp v252, v252, v252 quad_perm:[2,3,0,1] row_mask:0xf bank_mask:0xf bound_ctrl:1
	v_add_f32_dpp v253, v253, v253 quad_perm:[2,3,0,1] row_mask:0xf bank_mask:0xf bound_ctrl:1
	v_add_f32_dpp v254, v254, v254 quad_perm:[2,3,0,1] row_mask:0xf bank_mask:0xf bound_ctrl:1
	v_add_f32_dpp v255, v255, v255 quad_perm:[2,3,0,1] row_mask:0xf bank_mask:0xf bound_ctrl:1
	v_add_f32_dpp v248, v248, v248 row_half_mirror row_mask:0xf bank_mask:0xf bound_ctrl:1
	v_add_f32_dpp v249, v249, v249 row_half_mirror row_mask:0xf bank_mask:0xf bound_ctrl:1
	v_add_f32_dpp v250, v250, v250 row_half_mirror row_mask:0xf bank_mask:0xf bound_ctrl:1
	v_add_f32_dpp v251, v251, v251 row_half_mirror row_mask:0xf bank_mask:0xf bound_ctrl:1
	v_add_f32_dpp v252, v252, v252 row_half_mirror row_mask:0xf bank_mask:0xf bound_ctrl:1
	v_add_f32_dpp v253, v253, v253 row_half_mirror row_mask:0xf bank_mask:0xf bound_ctrl:1
	v_add_f32_dpp v254, v254, v254 row_half_mirror row_mask:0xf bank_mask:0xf bound_ctrl:1
	v_add_f32_dpp v255, v255, v255 row_half_mirror row_mask:0xf bank_mask:0xf bound_ctrl:1
	v_mov_b32_e32 v12, 0x358637bd
	v_fmamk_f32 v248, v248, 0x3c800000, v12
	v_fmamk_f32 v249, v249, 0x3c800000, v12
	v_fmamk_f32 v250, v250, 0x3c800000, v12
	v_fmamk_f32 v251, v251, 0x3c800000, v12
	v_fmamk_f32 v252, v252, 0x3c800000, v12
	v_fmamk_f32 v253, v253, 0x3c800000, v12
	v_fmamk_f32 v254, v254, 0x3c800000, v12
	v_fmamk_f32 v255, v255, 0x3c800000, v12
	v_rsq_f32_e32 v248, v248
	v_rsq_f32_e32 v249, v249
	v_rsq_f32_e32 v250, v250
	v_rsq_f32_e32 v251, v251
	v_rsq_f32_e32 v252, v252
	v_rsq_f32_e32 v253, v253
	v_rsq_f32_e32 v254, v254
	v_rsq_f32_e32 v255, v255
	v_mul_f32_e32 v248, 0x3e38aa3b, v248
	v_mul_f32_e32 v249, 0x3e38aa3b, v249
	v_mul_f32_e32 v250, 0x3e38aa3b, v250
	v_mul_f32_e32 v251, 0x3e38aa3b, v251
	v_mul_f32_e32 v252, 0x3e38aa3b, v252
	v_mul_f32_e32 v253, 0x3e38aa3b, v253
	v_mul_f32_e32 v254, 0x3e38aa3b, v254
	v_mul_f32_e32 v255, 0x3e38aa3b, v255
	v_lshlrev_b32_e32 v34, 16, v110
	v_and_b32_e32 v35, 0xffff0000, v110
	v_lshlrev_b32_e32 v36, 16, v111
	v_and_b32_e32 v37, 0xffff0000, v111
	v_lshlrev_b32_e32 v38, 16, v112
	v_and_b32_e32 v39, 0xffff0000, v112
	v_lshlrev_b32_e32 v52, 16, v113
	v_and_b32_e32 v53, 0xffff0000, v113
	v_pk_mul_f32 v[34:35], v[248:249], v[34:35] op_sel_hi:[0,1]
	v_pk_mul_f32 v[36:37], v[248:249], v[36:37] op_sel_hi:[0,1]
	v_pk_mul_f32 v[38:39], v[248:249], v[38:39] op_sel_hi:[0,1]
	v_pk_mul_f32 v[52:53], v[248:249], v[52:53] op_sel_hi:[0,1]
	v_pk_mul_f32 v[34:35], v[240:241], v[34:35]
	v_pk_mul_f32 v[36:37], v[242:243], v[36:37]
	v_pk_mul_f32 v[38:39], v[244:245], v[38:39]
	v_pk_mul_f32 v[52:53], v[246:247], v[52:53]
	v_cvt_pk_bf16_f32 v110, v34, v35
	v_cvt_pk_bf16_f32 v111, v36, v37
	v_cvt_pk_bf16_f32 v112, v38, v39
	v_cvt_pk_bf16_f32 v113, v52, v53
	global_store_dwordx4 v2, v[110:113], s[44:45]
	s_add_u32 s44, s44, 0x2000
	s_addc_u32 s45, s45, 0
	v_lshlrev_b32_e32 v34, 16, v114
; __device__ __forceinline__ float bflo(unsigned u) { return __uint_as_float(u << 16); }
; __device__ __forceinline__ float bfhi(unsigned u) { return __uint_as_float(u & 0xffff0000u); }
; DI float bflo(unsigned u) { return __uint_as_float(u << 16); }
; DI float bfhi(unsigned u) { return __uint_as_float(u & 0xffff0000u); }
; DI unsigned pk2(float lo, float hi) { f32x2_t v = {lo, hi}; bf16x2_t b = __builtin_convertvector(v, bf16x2_t); return __builtin_bit_cast(unsigned, b); }
; DI void fox_prep_unit(const Params& P, int n, unsigned char* lds, int tid) {
;     ...
; #pragma unroll
;         for (int i = 0; i < 8; ++i) { const f32x4 w0 = *(const f32x4*)(nw + 8 * i), w1 = *(const f32x4*)(nw + 8 * i + 4); u32x4 o;
;             o.x = pk2(bflo(raw[i].x) * rstd * w0.x, bfhi(raw[i].x) * rstd * w0.y); o.y = pk2(bflo(raw[i].y) * rstd * w0.z, bfhi(raw[i].y) * rstd * w0.w);
;             o.z = pk2(bflo(raw[i].z) * rstd * w1.x, bfhi(raw[i].z) * rstd * w1.y); o.w = pk2(bflo(raw[i].w) * rstd * w1.z, bfhi(raw[i].w) * rstd * w1.w);
;             *(u32x4*)(ptr + 8 * i) = o; }
	v_and_b32_e32 v35, 0xffff0000, v114
	v_lshlrev_b32_e32 v36, 16, v115
	v_and_b32_e32 v37, 0xffff0000, v115
	v_lshlrev_b32_e32 v38, 16, v116
	v_and_b32_e32 v39, 0xffff0000, v116
	v_lshlrev_b32_e32 v52, 16, v117
	v_and_b32_e32 v53, 0xffff0000, v117
	v_pk_mul_f32 v[34:35], v[248:249], v[34:35] op_sel:[1,0] op_sel_hi:[1,1]
	v_pk_mul_f32 v[36:37], v[248:249], v[36:37] op_sel:[1,0] op_sel_hi:[1,1]
	v_pk_mul_f32 v[38:39], v[248:249], v[38:39] op_sel:[1,0] op_sel_hi:[1,1]
	v_pk_mul_f32 v[52:53], v[248:249], v[52:53] op_sel:[1,0] op_sel_hi:[1,1]
	v_pk_mul_f32 v[34:35], v[240:241], v[34:35]
	v_pk_mul_f32 v[36:37], v[242:243], v[36:37]
	v_pk_mul_f32 v[38:39], v[244:245], v[38:39]
	v_pk_mul_f32 v[52:53], v[246:247], v[52:53]
	v_cvt_pk_bf16_f32 v114, v34, v35
	v_cvt_pk_bf16_f32 v115, v36, v37
	v_cvt_pk_bf16_f32 v116, v38, v39
	v_cvt_pk_bf16_f32 v117, v52, v53
	global_store_dwordx4 v2, v[114:117], s[44:45]
	s_add_u32 s44, s44, 0x2000
	s_addc_u32 s45, s45, 0
	global_load_dwordx4 v[110:113], v3, s[42:43]
	global_load_dwordx4 v[114:117], v3, s[42:43] offset:16
	v_lshlrev_b32_e32 v34, 16, v118
	v_and_b32_e32 v35, 0xffff0000, v118
	v_lshlrev_b32_e32 v36, 16, v119
	v_and_b32_e32 v37, 0xffff0000, v119
	v_lshlrev_b32_e32 v38, 16, v120
	v_and_b32_e32 v39, 0xffff0000, v120
	v_lshlrev_b32_e32 v52, 16, v121
	v_and_b32_e32 v53, 0xffff0000, v121
	v_pk_mul_f32 v[34:35], v[250:251], v[34:35] op_sel_hi:[0,1]
	v_pk_mul_f32 v[36:37], v[250:251], v[36:37] op_sel_hi:[0,1]
	v_pk_mul_f32 v[38:39], v[250:251], v[38:39] op_sel_hi:[0,1]
	v_pk_mul_f32 v[52:53], v[250:251], v[52:53] op_sel_hi:[0,1]
	v_pk_mul_f32 v[34:35], v[240:241], v[34:35]
	v_pk_mul_f32 v[36:37], v[242:243], v[36:37]
	v_pk_mul_f32 v[38:39], v[244:245], v[38:39]
	v_pk_mul_f32 v[52:53], v[246:247], v[52:53]
	v_cvt_pk_bf16_f32 v118, v34, v35
	v_cvt_pk_bf16_f32 v119, v36, v37
	v_cvt_pk_bf16_f32 v120, v38, v39
	v_cvt_pk_bf16_f32 v121, v52, v53
	global_store_dwordx4 v2, v[118:121], s[44:45]
	s_add_u32 s44, s44, 0x2000
	s_addc_u32 s45, s45, 0
	v_lshlrev_b32_e32 v34, 16, v122
	v_and_b32_e32 v35, 0xffff0000, v122
	v_lshlrev_b32_e32 v36, 16, v123
	v_and_b32_e32 v37, 0xffff0000, v123
	v_lshlrev_b32_e32 v38, 16, v124
	v_and_b32_e32 v39, 0xffff0000, v124
	v_lshlrev_b32_e32 v52, 16, v125
	v_and_b32_e32 v53, 0xffff0000, v125
	v_pk_mul_f32 v[34:35], v[250:251], v[34:35] op_sel:[1,0] op_sel_hi:[1,1]
	v_pk_mul_f32 v[36:37], v[250:251], v[36:37] op_sel:[1,0] op_sel_hi:[1,1]
	v_pk_mul_f32 v[38:39], v[250:251], v[38:39] op_sel:[1,0] op_sel_hi:[1,1]
	v_pk_mul_f32 v[52:53], v[250:251], v[52:53] op_sel:[1,0] op_sel_hi:[1,1]
	v_pk_mul_f32 v[34:35], v[240:241], v[34:35]
	v_pk_mul_f32 v[36:37], v[242:243], v[36:37]
	v_pk_mul_f32 v[38:39], v[244:245], v[38:39]
	v_pk_mul_f32 v[52:53], v[246:247], v[52:53]
	v_cvt_pk_bf16_f32 v122, v34, v35
	v_cvt_pk_bf16_f32 v123, v36, v37
	v_cvt_pk_bf16_f32 v124, v38, v39
	v_cvt_pk_bf16_f32 v125, v52, v53
	global_store_dwordx4 v2, v[122:125], s[44:45]
	s_add_u32 s44, s44, 0x2000
	s_addc_u32 s45, s45, 0
	v_lshlrev_b32_e32 v34, 16, v126
	v_and_b32_e32 v35, 0xffff0000, v126
	v_lshlrev_b32_e32 v36, 16, v127
	v_and_b32_e32 v37, 0xffff0000, v127
	v_lshlrev_b32_e32 v38, 16, v128
	v_and_b32_e32 v39, 0xffff0000, v128
	v_lshlrev_b32_e32 v52, 16, v129
	v_and_b32_e32 v53, 0xffff0000, v129
	v_pk_mul_f32 v[34:35], v[252:253], v[34:35] op_sel_hi:[0,1]
	v_pk_mul_f32 v[36:37], v[252:253], v[36:37] op_sel_hi:[0,1]
	v_pk_mul_f32 v[38:39], v[252:253], v[38:39] op_sel_hi:[0,1]
	v_pk_mul_f32 v[52:53], v[252:253], v[52:53] op_sel_hi:[0,1]
	v_pk_mul_f32 v[34:35], v[240:241], v[34:35]
	v_pk_mul_f32 v[36:37], v[242:243], v[36:37]
	v_pk_mul_f32 v[38:39], v[244:245], v[38:39]
	v_pk_mul_f32 v[52:53], v[246:247], v[52:53]
	v_cvt_pk_bf16_f32 v126, v34, v35
	v_cvt_pk_bf16_f32 v127, v36, v37
	v_cvt_pk_bf16_f32 v128, v38, v39
	v_cvt_pk_bf16_f32 v129, v52, v53
	global_store_dwordx4 v2, v[126:129], s[44:45]
	s_add_u32 s44, s44, 0x2000
	s_addc_u32 s45, s45, 0
	v_lshlrev_b32_e32 v34, 16, v130
	v_and_b32_e32 v35, 0xffff0000, v130
	v_lshlrev_b32_e32 v36, 16, v131
	v_and_b32_e32 v37, 0xffff0000, v131
	v_lshlrev_b32_e32 v38, 16, v132
	v_and_b32_e32 v39, 0xffff0000, v132
	v_lshlrev_b32_e32 v52, 16, v133
	v_and_b32_e32 v53, 0xffff0000, v133
	v_pk_mul_f32 v[34:35], v[252:253], v[34:35] op_sel:[1,0] op_sel_hi:[1,1]
	v_pk_mul_f32 v[36:37], v[252:253], v[36:37] op_sel:[1,0] op_sel_hi:[1,1]
	v_pk_mul_f32 v[38:39], v[252:253], v[38:39] op_sel:[1,0] op_sel_hi:[1,1]
	v_pk_mul_f32 v[52:53], v[252:253], v[52:53] op_sel:[1,0] op_sel_hi:[1,1]
	v_pk_mul_f32 v[34:35], v[240:241], v[34:35]
	v_pk_mul_f32 v[36:37], v[242:243], v[36:37]
	v_pk_mul_f32 v[38:39], v[244:245], v[38:39]
	v_pk_mul_f32 v[52:53], v[246:247], v[52:53]
	v_cvt_pk_bf16_f32 v130, v34, v35
	v_cvt_pk_bf16_f32 v131, v36, v37
	v_cvt_pk_bf16_f32 v132, v38, v39
	v_cvt_pk_bf16_f32 v133, v52, v53
	global_store_dwordx4 v2, v[130:133], s[44:45]
	s_add_u32 s44, s44, 0x2000
	s_addc_u32 s45, s45, 0
	v_lshlrev_b32_e32 v34, 16, v134
	v_and_b32_e32 v35, 0xffff0000, v134
	v_lshlrev_b32_e32 v36, 16, v135
	v_and_b32_e32 v37, 0xffff0000, v135
	v_lshlrev_b32_e32 v38, 16, v136
	v_and_b32_e32 v39, 0xffff0000, v136
	v_lshlrev_b32_e32 v52, 16, v137
	v_and_b32_e32 v53, 0xffff0000, v137
	v_pk_mul_f32 v[34:35], v[254:255], v[34:35] op_sel_hi:[0,1]
	v_pk_mul_f32 v[36:37], v[254:255], v[36:37] op_sel_hi:[0,1]
	v_pk_mul_f32 v[38:39], v[254:255], v[38:39] op_sel_hi:[0,1]
	v_pk_mul_f32 v[52:53], v[254:255], v[52:53] op_sel_hi:[0,1]
	v_pk_mul_f32 v[34:35], v[240:241], v[34:35]
	v_pk_mul_f32 v[36:37], v[242:243], v[36:37]
	v_pk_mul_f32 v[38:39], v[244:245], v[38:39]
	v_pk_mul_f32 v[52:53], v[246:247], v[52:53]
	v_cvt_pk_bf16_f32 v134, v34, v35
	v_cvt_pk_bf16_f32 v135, v36, v37
	v_cvt_pk_bf16_f32 v136, v38, v39
	v_cvt_pk_bf16_f32 v137, v52, v53
	global_store_dwordx4 v2, v[134:137], s[44:45]
	s_add_u32 s44, s44, 0x2000
	s_addc_u32 s45, s45, 0
	v_lshlrev_b32_e32 v34, 16, v138
	v_and_b32_e32 v35, 0xffff0000, v138
	v_lshlrev_b32_e32 v36, 16, v139
	v_and_b32_e32 v37, 0xffff0000, v139
	v_lshlrev_b32_e32 v38, 16, v140
	v_and_b32_e32 v39, 0xffff0000, v140
	v_lshlrev_b32_e32 v52, 16, v141
	v_and_b32_e32 v53, 0xffff0000, v141
	v_pk_mul_f32 v[34:35], v[254:255], v[34:35] op_sel:[1,0] op_sel_hi:[1,1]
	v_pk_mul_f32 v[36:37], v[254:255], v[36:37] op_sel:[1,0] op_sel_hi:[1,1]
	v_pk_mul_f32 v[38:39], v[254:255], v[38:39] op_sel:[1,0] op_sel_hi:[1,1]
	v_pk_mul_f32 v[52:53], v[254:255], v[52:53] op_sel:[1,0] op_sel_hi:[1,1]
	v_pk_mul_f32 v[34:35], v[240:241], v[34:35]
	v_pk_mul_f32 v[36:37], v[242:243], v[36:37]
	v_pk_mul_f32 v[38:39], v[244:245], v[38:39]
	v_pk_mul_f32 v[52:53], v[246:247], v[52:53]
	v_cvt_pk_bf16_f32 v138, v34, v35
	v_cvt_pk_bf16_f32 v139, v36, v37
	v_cvt_pk_bf16_f32 v140, v38, v39
	v_cvt_pk_bf16_f32 v141, v52, v53
	global_store_dwordx4 v2, v[138:141], s[44:45]
	s_add_u32 s44, s44, 0x2000
	s_addc_u32 s45, s45, 0
	s_waitcnt vmcnt(17)
; __device__ __forceinline__ float bflo(unsigned u) { return __uint_as_float(u << 16); }
; __device__ __forceinline__ float bfhi(unsigned u) { return __uint_as_float(u & 0xffff0000u); }
; DI float bflo(unsigned u) { return __uint_as_float(u << 16); }
; DI float bfhi(unsigned u) { return __uint_as_float(u & 0xffff0000u); }
; DI void fox_prep_unit(const Params& P, int n, unsigned char* lds, int tid) {
;     ...
;         u32x4 raw[8]; float ss = 0.f;
; #pragma unroll
;         for (int i = 0; i < 8; ++i) { raw[i] = *(const u32x4*)(ptr + 8 * i);
;             const float a0 = bflo(raw[i].x), a1 = bfhi(raw[i].x), a2 = bflo(raw[i].y), a3 = bfhi(raw[i].y), a4 = bflo(raw[i].z), a5 = bfhi(raw[i].z), a6 = bflo(raw[i].w), a7 = bfhi(raw[i].w);
;             ss += (a0 * a0 + a1 * a1) + (a2 * a2 + a3 * a3) + (a4 * a4 + a5 * a5) + (a6 * a6 + a7 * a7); }
;         const float rstd = rsqrtf(ss * (1.f / 64.f) + EPS) * sc;
	v_lshlrev_b32_e32 v34, 16, v88
	v_and_b32_e32 v35, 0xffff0000, v88
	v_lshlrev_b32_e32 v36, 16, v89
	v_and_b32_e32 v37, 0xffff0000, v89
	v_lshlrev_b32_e32 v38, 16, v90
	v_and_b32_e32 v39, 0xffff0000, v90
	v_lshlrev_b32_e32 v52, 16, v91
	v_and_b32_e32 v53, 0xffff0000, v91
	v_mul_f32_e32 v248, v34, v34
	v_fmac_f32_e32 v248, v35, v35
	v_fmac_f32_e32 v248, v36, v36
	v_fmac_f32_e32 v248, v37, v37
	v_fmac_f32_e32 v248, v38, v38
	v_fmac_f32_e32 v248, v39, v39
	v_fmac_f32_e32 v248, v52, v52
	v_fmac_f32_e32 v248, v53, v53
	s_waitcnt vmcnt(16)
	v_lshlrev_b32_e32 v34, 16, v92
	v_and_b32_e32 v35, 0xffff0000, v92
	v_lshlrev_b32_e32 v36, 16, v93
	v_and_b32_e32 v37, 0xffff0000, v93
	v_lshlrev_b32_e32 v38, 16, v94
	v_and_b32_e32 v39, 0xffff0000, v94
	v_lshlrev_b32_e32 v52, 16, v95
	v_and_b32_e32 v53, 0xffff0000, v95
	v_mul_f32_e32 v249, v34, v34
	v_fmac_f32_e32 v249, v35, v35
	v_fmac_f32_e32 v249, v36, v36
	v_fmac_f32_e32 v249, v37, v37
	v_fmac_f32_e32 v249, v38, v38
	v_fmac_f32_e32 v249, v39, v39
	v_fmac_f32_e32 v249, v52, v52
	v_fmac_f32_e32 v249, v53, v53
	s_waitcnt vmcnt(15)
	v_lshlrev_b32_e32 v34, 16, v96
	v_and_b32_e32 v35, 0xffff0000, v96
	v_lshlrev_b32_e32 v36, 16, v97
	v_and_b32_e32 v37, 0xffff0000, v97
	v_lshlrev_b32_e32 v38, 16, v98
	v_and_b32_e32 v39, 0xffff0000, v98
	v_lshlrev_b32_e32 v52, 16, v99
	v_and_b32_e32 v53, 0xffff0000, v99
	v_mul_f32_e32 v250, v34, v34
	v_fmac_f32_e32 v250, v35, v35
	v_fmac_f32_e32 v250, v36, v36
	v_fmac_f32_e32 v250, v37, v37
	v_fmac_f32_e32 v250, v38, v38
	v_fmac_f32_e32 v250, v39, v39
	v_fmac_f32_e32 v250, v52, v52
	v_fmac_f32_e32 v250, v53, v53
	s_waitcnt vmcnt(14)
	v_lshlrev_b32_e32 v34, 16, v100
	v_and_b32_e32 v35, 0xffff0000, v100
	v_lshlrev_b32_e32 v36, 16, v101
	v_and_b32_e32 v37, 0xffff0000, v101
	v_lshlrev_b32_e32 v38, 16, v102
	v_and_b32_e32 v39, 0xffff0000, v102
	v_lshlrev_b32_e32 v52, 16, v103
	v_and_b32_e32 v53, 0xffff0000, v103
	v_mul_f32_e32 v251, v34, v34
	v_fmac_f32_e32 v251, v35, v35
	v_fmac_f32_e32 v251, v36, v36
	v_fmac_f32_e32 v251, v37, v37
	v_fmac_f32_e32 v251, v38, v38
	v_fmac_f32_e32 v251, v39, v39
	v_fmac_f32_e32 v251, v52, v52
	v_fmac_f32_e32 v251, v53, v53
	s_waitcnt vmcnt(13)
	v_lshlrev_b32_e32 v34, 16, v44
	v_and_b32_e32 v35, 0xffff0000, v44
	v_lshlrev_b32_e32 v36, 16, v45
	v_and_b32_e32 v37, 0xffff0000, v45
	v_lshlrev_b32_e32 v38, 16, v46
	v_and_b32_e32 v39, 0xffff0000, v46
	v_lshlrev_b32_e32 v52, 16, v47
	v_and_b32_e32 v53, 0xffff0000, v47
	v_mul_f32_e32 v252, v34, v34
	v_fmac_f32_e32 v252, v35, v35
	v_fmac_f32_e32 v252, v36, v36
	v_fmac_f32_e32 v252, v37, v37
	v_fmac_f32_e32 v252, v38, v38
	v_fmac_f32_e32 v252, v39, v39
	v_fmac_f32_e32 v252, v52, v52
	v_fmac_f32_e32 v252, v53, v53
	s_waitcnt vmcnt(12)
	v_lshlrev_b32_e32 v34, 16, v48
	v_and_b32_e32 v35, 0xffff0000, v48
	v_lshlrev_b32_e32 v36, 16, v49
	v_and_b32_e32 v37, 0xffff0000, v49
	v_lshlrev_b32_e32 v38, 16, v50
	v_and_b32_e32 v39, 0xffff0000, v50
	v_lshlrev_b32_e32 v52, 16, v51
	v_and_b32_e32 v53, 0xffff0000, v51
	v_mul_f32_e32 v253, v34, v34
	v_fmac_f32_e32 v253, v35, v35
	v_fmac_f32_e32 v253, v36, v36
	v_fmac_f32_e32 v253, v37, v37
	v_fmac_f32_e32 v253, v38, v38
	v_fmac_f32_e32 v253, v39, v39
	v_fmac_f32_e32 v253, v52, v52
	v_fmac_f32_e32 v253, v53, v53
	s_waitcnt vmcnt(11)
	v_lshlrev_b32_e32 v34, 16, v4
	v_and_b32_e32 v35, 0xffff0000, v4
	v_lshlrev_b32_e32 v36, 16, v5
	v_and_b32_e32 v37, 0xffff0000, v5
	v_lshlrev_b32_e32 v38, 16, v6
	v_and_b32_e32 v39, 0xffff0000, v6
	v_lshlrev_b32_e32 v52, 16, v7
	v_and_b32_e32 v53, 0xffff0000, v7
	v_mul_f32_e32 v254, v34, v34
	v_fmac_f32_e32 v254, v35, v35
	v_fmac_f32_e32 v254, v36, v36
	v_fmac_f32_e32 v254, v37, v37
	v_fmac_f32_e32 v254, v38, v38
	v_fmac_f32_e32 v254, v39, v39
	v_fmac_f32_e32 v254, v52, v52
	v_fmac_f32_e32 v254, v53, v53
	s_waitcnt vmcnt(10)
	v_lshlrev_b32_e32 v34, 16, v8
	v_and_b32_e32 v35, 0xffff0000, v8
	v_lshlrev_b32_e32 v36, 16, v9
	v_and_b32_e32 v37, 0xffff0000, v9
	v_lshlrev_b32_e32 v38, 16, v10
	v_and_b32_e32 v39, 0xffff0000, v10
	v_lshlrev_b32_e32 v52, 16, v11
	v_and_b32_e32 v53, 0xffff0000, v11
	v_mul_f32_e32 v255, v34, v34
	v_fmac_f32_e32 v255, v35, v35
	v_fmac_f32_e32 v255, v36, v36
	v_fmac_f32_e32 v255, v37, v37
	v_fmac_f32_e32 v255, v38, v38
	v_fmac_f32_e32 v255, v39, v39
	v_fmac_f32_e32 v255, v52, v52
	v_fmac_f32_e32 v255, v53, v53
	v_add_f32_dpp v248, v248, v248 quad_perm:[1,0,3,2] row_mask:0xf bank_mask:0xf bound_ctrl:1
	v_add_f32_dpp v249, v249, v249 quad_perm:[1,0,3,2] row_mask:0xf bank_mask:0xf bound_ctrl:1
	v_add_f32_dpp v250, v250, v250 quad_perm:[1,0,3,2] row_mask:0xf bank_mask:0xf bound_ctrl:1
	v_add_f32_dpp v251, v251, v251 quad_perm:[1,0,3,2] row_mask:0xf bank_mask:0xf bound_ctrl:1
	v_add_f32_dpp v252, v252, v252 quad_perm:[1,0,3,2] row_mask:0xf bank_mask:0xf bound_ctrl:1
	v_add_f32_dpp v253, v253, v253 quad_perm:[1,0,3,2] row_mask:0xf bank_mask:0xf bound_ctrl:1
	v_add_f32_dpp v254, v254, v254 quad_perm:[1,0,3,2] row_mask:0xf bank_mask:0xf bound_ctrl:1
	v_add_f32_dpp v255, v255, v255 quad_perm:[1,0,3,2] row_mask:0xf bank_mask:0xf bound_ctrl:1
	v_add_f32_dpp v248, v248, v248 quad_perm:[2,3,0,1] row_mask:0xf bank_mask:0xf bound_ctrl:1
	v_add_f32_dpp v249, v249, v249 quad_perm:[2,3,0,1] row_mask:0xf bank_mask:0xf bound_ctrl:1
	v_add_f32_dpp v250, v250, v250 quad_perm:[2,3,0,1] row_mask:0xf bank_mask:0xf bound_ctrl:1
	v_add_f32_dpp v251, v251, v251 quad_perm:[2,3,0,1] row_mask:0xf bank_mask:0xf bound_ctrl:1
	v_add_f32_dpp v252, v252, v252 quad_perm:[2,3,0,1] row_mask:0xf bank_mask:0xf bound_ctrl:1
	v_add_f32_dpp v253, v253, v253 quad_perm:[2,3,0,1] row_mask:0xf bank_mask:0xf bound_ctrl:1
	v_add_f32_dpp v254, v254, v254 quad_perm:[2,3,0,1] row_mask:0xf bank_mask:0xf bound_ctrl:1
; __device__ __forceinline__ float bflo(unsigned u) { return __uint_as_float(u << 16); }
; __device__ __forceinline__ float bfhi(unsigned u) { return __uint_as_float(u & 0xffff0000u); }
; DI float bflo(unsigned u) { return __uint_as_float(u << 16); }
; DI float bfhi(unsigned u) { return __uint_as_float(u & 0xffff0000u); }
; DI unsigned pk2(float lo, float hi) { f32x2_t v = {lo, hi}; bf16x2_t b = __builtin_convertvector(v, bf16x2_t); return __builtin_bit_cast(unsigned, b); }
; DI void fox_prep_unit(const Params& P, int n, unsigned char* lds, int tid) {
;     ...
;         const float rstd = rsqrtf(ss * (1.f / 64.f) + EPS) * sc;
; #pragma unroll
;         for (int i = 0; i < 8; ++i) { const f32x4 w0 = *(const f32x4*)(nw + 8 * i), w1 = *(const f32x4*)(nw + 8 * i + 4); u32x4 o;
;             o.x = pk2(bflo(raw[i].x) * rstd * w0.x, bfhi(raw[i].x) * rstd * w0.y); o.y = pk2(bflo(raw[i].y) * rstd * w0.z, bfhi(raw[i].y) * rstd * w0.w);
;             o.z = pk2(bflo(raw[i].z) * rstd * w1.x, bfhi(raw[i].z) * rstd * w1.y); o.w = pk2(bflo(raw[i].w) * rstd * w1.z, bfhi(raw[i].w) * rstd * w1.w);
;             *(u32x4*)(ptr + 8 * i) = o; }
	v_add_f32_dpp v255, v255, v255 quad_perm:[2,3,0,1] row_mask:0xf bank_mask:0xf bound_ctrl:1
	v_add_f32_dpp v248, v248, v248 row_half_mirror row_mask:0xf bank_mask:0xf bound_ctrl:1
	v_add_f32_dpp v249, v249, v249 row_half_mirror row_mask:0xf bank_mask:0xf bound_ctrl:1
	v_add_f32_dpp v250, v250, v250 row_half_mirror row_mask:0xf bank_mask:0xf bound_ctrl:1
	v_add_f32_dpp v251, v251, v251 row_half_mirror row_mask:0xf bank_mask:0xf bound_ctrl:1
	v_add_f32_dpp v252, v252, v252 row_half_mirror row_mask:0xf bank_mask:0xf bound_ctrl:1
	v_add_f32_dpp v253, v253, v253 row_half_mirror row_mask:0xf bank_mask:0xf bound_ctrl:1
	v_add_f32_dpp v254, v254, v254 row_half_mirror row_mask:0xf bank_mask:0xf bound_ctrl:1
	v_add_f32_dpp v255, v255, v255 row_half_mirror row_mask:0xf bank_mask:0xf bound_ctrl:1
	v_mov_b32_e32 v12, 0x358637bd
	v_fmamk_f32 v248, v248, 0x3c800000, v12
	v_fmamk_f32 v249, v249, 0x3c800000, v12
	v_fmamk_f32 v250, v250, 0x3c800000, v12
	v_fmamk_f32 v251, v251, 0x3c800000, v12
	v_fmamk_f32 v252, v252, 0x3c800000, v12
	v_fmamk_f32 v253, v253, 0x3c800000, v12
	v_fmamk_f32 v254, v254, 0x3c800000, v12
	v_fmamk_f32 v255, v255, 0x3c800000, v12
	v_rsq_f32_e32 v248, v248
	v_rsq_f32_e32 v249, v249
	v_rsq_f32_e32 v250, v250
	v_rsq_f32_e32 v251, v251
	v_rsq_f32_e32 v252, v252
	v_rsq_f32_e32 v253, v253
	v_rsq_f32_e32 v254, v254
	v_rsq_f32_e32 v255, v255
	s_nop 0
	s_waitcnt vmcnt(6)
	v_lshlrev_b32_e32 v34, 16, v88
	v_and_b32_e32 v35, 0xffff0000, v88
	v_lshlrev_b32_e32 v36, 16, v89
	v_and_b32_e32 v37, 0xffff0000, v89
	v_lshlrev_b32_e32 v38, 16, v90
	v_and_b32_e32 v39, 0xffff0000, v90
	v_lshlrev_b32_e32 v52, 16, v91
	v_and_b32_e32 v53, 0xffff0000, v91
	v_pk_mul_f32 v[34:35], v[248:249], v[34:35] op_sel_hi:[0,1]
	v_pk_mul_f32 v[36:37], v[248:249], v[36:37] op_sel_hi:[0,1]
	v_pk_mul_f32 v[38:39], v[248:249], v[38:39] op_sel_hi:[0,1]
	v_pk_mul_f32 v[52:53], v[248:249], v[52:53] op_sel_hi:[0,1]
	v_pk_mul_f32 v[34:35], v[110:111], v[34:35]
	v_pk_mul_f32 v[36:37], v[112:113], v[36:37]
	v_pk_mul_f32 v[38:39], v[114:115], v[38:39]
	v_pk_mul_f32 v[52:53], v[116:117], v[52:53]
	v_cvt_pk_bf16_f32 v88, v34, v35
	v_cvt_pk_bf16_f32 v89, v36, v37
	v_cvt_pk_bf16_f32 v90, v38, v39
	v_cvt_pk_bf16_f32 v91, v52, v53
	global_store_dwordx4 v2, v[88:91], s[46:47]
	s_add_u32 s46, s46, 0x2000
	s_addc_u32 s47, s47, 0
	v_lshlrev_b32_e32 v34, 16, v92
	v_and_b32_e32 v35, 0xffff0000, v92
	v_lshlrev_b32_e32 v36, 16, v93
	v_and_b32_e32 v37, 0xffff0000, v93
	v_lshlrev_b32_e32 v38, 16, v94
	v_and_b32_e32 v39, 0xffff0000, v94
	v_lshlrev_b32_e32 v52, 16, v95
	v_and_b32_e32 v53, 0xffff0000, v95
	v_pk_mul_f32 v[34:35], v[248:249], v[34:35] op_sel:[1,0] op_sel_hi:[1,1]
	v_pk_mul_f32 v[36:37], v[248:249], v[36:37] op_sel:[1,0] op_sel_hi:[1,1]
	v_pk_mul_f32 v[38:39], v[248:249], v[38:39] op_sel:[1,0] op_sel_hi:[1,1]
	v_pk_mul_f32 v[52:53], v[248:249], v[52:53] op_sel:[1,0] op_sel_hi:[1,1]
	v_pk_mul_f32 v[34:35], v[110:111], v[34:35]
	v_pk_mul_f32 v[36:37], v[112:113], v[36:37]
	v_pk_mul_f32 v[38:39], v[114:115], v[38:39]
	v_pk_mul_f32 v[52:53], v[116:117], v[52:53]
	v_cvt_pk_bf16_f32 v92, v34, v35
	v_cvt_pk_bf16_f32 v93, v36, v37
	v_cvt_pk_bf16_f32 v94, v38, v39
	v_cvt_pk_bf16_f32 v95, v52, v53
	global_store_dwordx4 v2, v[92:95], s[46:47]
	s_add_u32 s46, s46, 0x2000
	s_addc_u32 s47, s47, 0
	v_lshlrev_b32_e32 v34, 16, v96
	v_and_b32_e32 v35, 0xffff0000, v96
	v_lshlrev_b32_e32 v36, 16, v97
	v_and_b32_e32 v37, 0xffff0000, v97
	v_lshlrev_b32_e32 v38, 16, v98
	v_and_b32_e32 v39, 0xffff0000, v98
	v_lshlrev_b32_e32 v52, 16, v99
	v_and_b32_e32 v53, 0xffff0000, v99
	v_pk_mul_f32 v[34:35], v[250:251], v[34:35] op_sel_hi:[0,1]
	v_pk_mul_f32 v[36:37], v[250:251], v[36:37] op_sel_hi:[0,1]
	v_pk_mul_f32 v[38:39], v[250:251], v[38:39] op_sel_hi:[0,1]
	v_pk_mul_f32 v[52:53], v[250:251], v[52:53] op_sel_hi:[0,1]
	v_pk_mul_f32 v[34:35], v[110:111], v[34:35]
	v_pk_mul_f32 v[36:37], v[112:113], v[36:37]
	v_pk_mul_f32 v[38:39], v[114:115], v[38:39]
	v_pk_mul_f32 v[52:53], v[116:117], v[52:53]
	v_cvt_pk_bf16_f32 v96, v34, v35
	v_cvt_pk_bf16_f32 v97, v36, v37
	v_cvt_pk_bf16_f32 v98, v38, v39
	v_cvt_pk_bf16_f32 v99, v52, v53
	global_store_dwordx4 v2, v[96:99], s[46:47]
	s_add_u32 s46, s46, 0x2000
	s_addc_u32 s47, s47, 0
	v_lshlrev_b32_e32 v34, 16, v100
	v_and_b32_e32 v35, 0xffff0000, v100
	v_lshlrev_b32_e32 v36, 16, v101
	v_and_b32_e32 v37, 0xffff0000, v101
	v_lshlrev_b32_e32 v38, 16, v102
	v_and_b32_e32 v39, 0xffff0000, v102
	v_lshlrev_b32_e32 v52, 16, v103
	v_and_b32_e32 v53, 0xffff0000, v103
	v_pk_mul_f32 v[34:35], v[250:251], v[34:35] op_sel:[1,0] op_sel_hi:[1,1]
	v_pk_mul_f32 v[36:37], v[250:251], v[36:37] op_sel:[1,0] op_sel_hi:[1,1]
	v_pk_mul_f32 v[38:39], v[250:251], v[38:39] op_sel:[1,0] op_sel_hi:[1,1]
	v_pk_mul_f32 v[52:53], v[250:251], v[52:53] op_sel:[1,0] op_sel_hi:[1,1]
	v_pk_mul_f32 v[34:35], v[110:111], v[34:35]
	v_pk_mul_f32 v[36:37], v[112:113], v[36:37]
	v_pk_mul_f32 v[38:39], v[114:115], v[38:39]
	v_pk_mul_f32 v[52:53], v[116:117], v[52:53]
	v_cvt_pk_bf16_f32 v100, v34, v35
	v_cvt_pk_bf16_f32 v101, v36, v37
	v_cvt_pk_bf16_f32 v102, v38, v39
	v_cvt_pk_bf16_f32 v103, v52, v53
	global_store_dwordx4 v2, v[100:103], s[46:47]
	s_add_u32 s46, s46, 0x2000
	s_addc_u32 s47, s47, 0
	v_lshlrev_b32_e32 v34, 16, v44
	v_and_b32_e32 v35, 0xffff0000, v44
	v_lshlrev_b32_e32 v36, 16, v45
	v_and_b32_e32 v37, 0xffff0000, v45
	v_lshlrev_b32_e32 v38, 16, v46
	v_and_b32_e32 v39, 0xffff0000, v46
	v_lshlrev_b32_e32 v52, 16, v47
	v_and_b32_e32 v53, 0xffff0000, v47
	v_pk_mul_f32 v[34:35], v[252:253], v[34:35] op_sel_hi:[0,1]
	v_pk_mul_f32 v[36:37], v[252:253], v[36:37] op_sel_hi:[0,1]
	v_pk_mul_f32 v[38:39], v[252:253], v[38:39] op_sel_hi:[0,1]
; __device__ __forceinline__ float bflo(unsigned u) { return __uint_as_float(u << 16); }
; __device__ __forceinline__ float bfhi(unsigned u) { return __uint_as_float(u & 0xffff0000u); }
; DI float bflo(unsigned u) { return __uint_as_float(u << 16); }
; DI float bfhi(unsigned u) { return __uint_as_float(u & 0xffff0000u); }
; DI unsigned pk2(float lo, float hi) { f32x2_t v = {lo, hi}; bf16x2_t b = __builtin_convertvector(v, bf16x2_t); return __builtin_bit_cast(unsigned, b); }
; DI void fox_prep_unit(const Params& P, int n, unsigned char* lds, int tid) {
;     ...
;         for (int i = 0; i < 8; ++i) { const f32x4 w0 = *(const f32x4*)(nw + 8 * i), w1 = *(const f32x4*)(nw + 8 * i + 4); u32x4 o;
;             o.x = pk2(bflo(raw[i].x) * rstd * w0.x, bfhi(raw[i].x) * rstd * w0.y); o.y = pk2(bflo(raw[i].y) * rstd * w0.z, bfhi(raw[i].y) * rstd * w0.w);
;             o.z = pk2(bflo(raw[i].z) * rstd * w1.x, bfhi(raw[i].z) * rstd * w1.y); o.w = pk2(bflo(raw[i].w) * rstd * w1.z, bfhi(raw[i].w) * rstd * w1.w);
;             *(u32x4*)(ptr + 8 * i) = o; }
	v_pk_mul_f32 v[52:53], v[252:253], v[52:53] op_sel_hi:[0,1]
	v_pk_mul_f32 v[34:35], v[110:111], v[34:35]
	v_pk_mul_f32 v[36:37], v[112:113], v[36:37]
	v_pk_mul_f32 v[38:39], v[114:115], v[38:39]
	v_pk_mul_f32 v[52:53], v[116:117], v[52:53]
	v_cvt_pk_bf16_f32 v44, v34, v35
	v_cvt_pk_bf16_f32 v45, v36, v37
	v_cvt_pk_bf16_f32 v46, v38, v39
	v_cvt_pk_bf16_f32 v47, v52, v53
	global_store_dwordx4 v2, v[44:47], s[46:47]
	s_add_u32 s46, s46, 0x2000
	s_addc_u32 s47, s47, 0
	v_lshlrev_b32_e32 v34, 16, v48
	v_and_b32_e32 v35, 0xffff0000, v48
	v_lshlrev_b32_e32 v36, 16, v49
	v_and_b32_e32 v37, 0xffff0000, v49
	v_lshlrev_b32_e32 v38, 16, v50
	v_and_b32_e32 v39, 0xffff0000, v50
	v_lshlrev_b32_e32 v52, 16, v51
	v_and_b32_e32 v53, 0xffff0000, v51
	v_pk_mul_f32 v[34:35], v[252:253], v[34:35] op_sel:[1,0] op_sel_hi:[1,1]
	v_pk_mul_f32 v[36:37], v[252:253], v[36:37] op_sel:[1,0] op_sel_hi:[1,1]
	v_pk_mul_f32 v[38:39], v[252:253], v[38:39] op_sel:[1,0] op_sel_hi:[1,1]
	v_pk_mul_f32 v[52:53], v[252:253], v[52:53] op_sel:[1,0] op_sel_hi:[1,1]
	v_pk_mul_f32 v[34:35], v[110:111], v[34:35]
	v_pk_mul_f32 v[36:37], v[112:113], v[36:37]
	v_pk_mul_f32 v[38:39], v[114:115], v[38:39]
	v_pk_mul_f32 v[52:53], v[116:117], v[52:53]
	v_cvt_pk_bf16_f32 v48, v34, v35
	v_cvt_pk_bf16_f32 v49, v36, v37
	v_cvt_pk_bf16_f32 v50, v38, v39
	v_cvt_pk_bf16_f32 v51, v52, v53
	global_store_dwordx4 v2, v[48:51], s[46:47]
	s_add_u32 s46, s46, 0x2000
	s_addc_u32 s47, s47, 0
	v_lshlrev_b32_e32 v34, 16, v4
	v_and_b32_e32 v35, 0xffff0000, v4
	v_lshlrev_b32_e32 v36, 16, v5
	v_and_b32_e32 v37, 0xffff0000, v5
	v_lshlrev_b32_e32 v38, 16, v6
	v_and_b32_e32 v39, 0xffff0000, v6
	v_lshlrev_b32_e32 v52, 16, v7
	v_and_b32_e32 v53, 0xffff0000, v7
	v_pk_mul_f32 v[34:35], v[254:255], v[34:35] op_sel_hi:[0,1]
	v_pk_mul_f32 v[36:37], v[254:255], v[36:37] op_sel_hi:[0,1]
	v_pk_mul_f32 v[38:39], v[254:255], v[38:39] op_sel_hi:[0,1]
	v_pk_mul_f32 v[52:53], v[254:255], v[52:53] op_sel_hi:[0,1]
	v_pk_mul_f32 v[34:35], v[110:111], v[34:35]
	v_pk_mul_f32 v[36:37], v[112:113], v[36:37]
	v_pk_mul_f32 v[38:39], v[114:115], v[38:39]
	v_pk_mul_f32 v[52:53], v[116:117], v[52:53]
	v_cvt_pk_bf16_f32 v4, v34, v35
	v_cvt_pk_bf16_f32 v5, v36, v37
	v_cvt_pk_bf16_f32 v6, v38, v39
	v_cvt_pk_bf16_f32 v7, v52, v53
	global_store_dwordx4 v2, v[4:7], s[46:47]
	s_add_u32 s46, s46, 0x2000
	s_addc_u32 s47, s47, 0
	v_lshlrev_b32_e32 v34, 16, v8
	v_and_b32_e32 v35, 0xffff0000, v8
	v_lshlrev_b32_e32 v36, 16, v9
	v_and_b32_e32 v37, 0xffff0000, v9
	v_lshlrev_b32_e32 v38, 16, v10
	v_and_b32_e32 v39, 0xffff0000, v10
	v_lshlrev_b32_e32 v52, 16, v11
	v_and_b32_e32 v53, 0xffff0000, v11
	v_pk_mul_f32 v[34:35], v[254:255], v[34:35] op_sel:[1,0] op_sel_hi:[1,1]
	v_pk_mul_f32 v[36:37], v[254:255], v[36:37] op_sel:[1,0] op_sel_hi:[1,1]
	v_pk_mul_f32 v[38:39], v[254:255], v[38:39] op_sel:[1,0] op_sel_hi:[1,1]
	v_pk_mul_f32 v[52:53], v[254:255], v[52:53] op_sel:[1,0] op_sel_hi:[1,1]
	v_pk_mul_f32 v[34:35], v[110:111], v[34:35]
	v_pk_mul_f32 v[36:37], v[112:113], v[36:37]
	v_pk_mul_f32 v[38:39], v[114:115], v[38:39]
	v_pk_mul_f32 v[52:53], v[116:117], v[52:53]
	v_cvt_pk_bf16_f32 v8, v34, v35
	v_cvt_pk_bf16_f32 v9, v36, v37
	v_cvt_pk_bf16_f32 v10, v38, v39
	v_cvt_pk_bf16_f32 v11, v52, v53
	global_store_dwordx4 v2, v[8:11], s[46:47]
	s_add_u32 s46, s46, 0x2000
	s_addc_u32 s47, s47, 0
	s_waitcnt vmcnt(30)
; DI float softplusf(float v) { return v > 20.f ? v : __logf(1.0f + __expf(v)); }
; #define LDSFENCE() asm volatile("s_waitcnt lgkmcnt(0)" ::: "memory")
; DI void fox_prep_unit(const Params& P, int n, unsigned char* lds, int tid) {
;     ...
;     { bf16_t* tile = (bf16_t*)(lds + h * 9216);
; #pragma unroll
;       for (int i = 0; i < 8; ++i) { const u32x4 r = *(const u32x4*)(FV + 8 * i);
;           tile[(8 * i + 0) * 72 + t] = (bf16_t)(r.x & 0xffffu); tile[(8 * i + 1) * 72 + t] = (bf16_t)(r.x >> 16);
;           tile[(8 * i + 2) * 72 + t] = (bf16_t)(r.y & 0xffffu); tile[(8 * i + 3) * 72 + t] = (bf16_t)(r.y >> 16);
;           tile[(8 * i + 4) * 72 + t] = (bf16_t)(r.z & 0xffffu); tile[(8 * i + 5) * 72 + t] = (bf16_t)(r.z >> 16);
;           tile[(8 * i + 6) * 72 + t] = (bf16_t)(r.w & 0xffffu); tile[(8 * i + 7) * 72 + t] = (bf16_t)(r.w >> 16); }
;       LDSFENCE();
;       bf16_t* VT = (bf16_t*)(ws + WS_VT) + (size_t)(h * 64) * SEQ + (size_t)n * 64;
; #pragma unroll
;       for (int k = 0; k < 8; ++k) { const int idx = t + 64 * k, d = idx >> 3, c = idx & 7;
;           *(u32x4*)(VT + (size_t)d * SEQ + 8 * c) = *(const u32x4*)(tile + d * 72 + 8 * c); }
;       LDSFENCE(); }
;     { const float f = ((const float*)(ws + WS_SMALL))[(size_t)tok * 32 + 16 + h] + P.in[8][h];
;       float v = -softplusf(-f) * 1.4426950408889634f;
;       v = wave_incl_scan(v);
;       ((float*)(ws + WS_CL))[(size_t)h * SEQ + tok] = v;
;       if (t == 63) ((float*)(ws + WS_CT))[h * 256 + n] = v; }
	s_nop 0
	ds_write_b16 v104, v30
	ds_write_b16_d16_hi v104, v30 offset:144
	ds_write_b16 v104, v31 offset:288
	ds_write_b16_d16_hi v104, v31 offset:432
	ds_write_b16 v104, v32 offset:576
	ds_write_b16_d16_hi v104, v32 offset:720
	ds_write_b16 v104, v33 offset:864
	ds_write_b16_d16_hi v104, v33 offset:1008
	ds_write_b16 v104, v40 offset:1152
	ds_write_b16_d16_hi v104, v40 offset:1296
	ds_write_b16 v104, v41 offset:1440
	ds_write_b16_d16_hi v104, v41 offset:1584
	ds_write_b16 v104, v42 offset:1728
	ds_write_b16_d16_hi v104, v42 offset:1872
	ds_write_b16 v104, v43 offset:2016
	ds_write_b16_d16_hi v104, v43 offset:2160
	ds_write_b16 v104, v54 offset:2304
	ds_write_b16_d16_hi v104, v54 offset:2448
	ds_write_b16 v104, v55 offset:2592
	ds_write_b16_d16_hi v104, v55 offset:2736
	ds_write_b16 v104, v56 offset:2880
	ds_write_b16_d16_hi v104, v56 offset:3024
	ds_write_b16 v104, v57 offset:3168
	ds_write_b16_d16_hi v104, v57 offset:3312
	ds_write_b16 v104, v58 offset:3456
	ds_write_b16_d16_hi v104, v58 offset:3600
	ds_write_b16 v104, v59 offset:3744
	ds_write_b16_d16_hi v104, v59 offset:3888
	ds_write_b16 v104, v60 offset:4032
	ds_write_b16_d16_hi v104, v60 offset:4176
	ds_write_b16 v104, v61 offset:4320
	ds_write_b16_d16_hi v104, v61 offset:4464
	ds_write_b16 v104, v62 offset:4608
	ds_write_b16_d16_hi v104, v62 offset:4752
	ds_write_b16 v104, v63 offset:4896
	ds_write_b16_d16_hi v104, v63 offset:5040
	ds_write_b16 v104, v64 offset:5184
	ds_write_b16_d16_hi v104, v64 offset:5328
	ds_write_b16 v104, v65 offset:5472
	ds_write_b16_d16_hi v104, v65 offset:5616
	ds_write_b16 v104, v66 offset:5760
	ds_write_b16_d16_hi v104, v66 offset:5904
	ds_write_b16 v104, v67 offset:6048
	ds_write_b16_d16_hi v104, v67 offset:6192
	ds_write_b16 v104, v68 offset:6336
	ds_write_b16_d16_hi v104, v68 offset:6480
	ds_write_b16 v104, v69 offset:6624
	ds_write_b16_d16_hi v104, v69 offset:6768
	ds_write_b16 v104, v70 offset:6912
	ds_write_b16_d16_hi v104, v70 offset:7056
	ds_write_b16 v104, v71 offset:7200
	ds_write_b16_d16_hi v104, v71 offset:7344
	ds_write_b16 v104, v72 offset:7488
	ds_write_b16_d16_hi v104, v72 offset:7632
	ds_write_b16 v104, v73 offset:7776
	ds_write_b16_d16_hi v104, v73 offset:7920
	ds_write_b16 v104, v74 offset:8064
	ds_write_b16_d16_hi v104, v74 offset:8208
	ds_write_b16 v104, v75 offset:8352
	ds_write_b16_d16_hi v104, v75 offset:8496
	ds_write_b16 v104, v76 offset:8640
	ds_write_b16_d16_hi v104, v76 offset:8784
	ds_write_b16 v104, v77 offset:8928
	ds_write_b16_d16_hi v104, v77 offset:9072
	v_add_co_u32_e32 v50, vcc, s22, v28
	v_lshlrev_b64 v[88:89], 7, v[26:27]
	s_nop 0
	s_nop 1
	v_addc_co_u32_e32 v51, vcc, 0, v29, vcc
	v_add_co_u32_e32 v52, vcc, s23, v28
	v_lshl_add_u64 v[88:89], v[20:21], 0, v[88:89]
	s_nop 0
	s_nop 1
	v_addc_co_u32_e32 v53, vcc, 0, v29, vcc
	s_waitcnt lgkmcnt(0)
	ds_read_b128 v[2:5], v107
	ds_read_b128 v[6:9], v107 offset:1152
	ds_read_b128 v[10:13], v107 offset:2304
	ds_read_b128 v[30:33], v107 offset:3456
	ds_read_b128 v[34:37], v107 offset:4608
	ds_read_b128 v[38:41], v107 offset:5760
	ds_read_b128 v[42:45], v107 offset:6912
	ds_read_b128 v[46:49], v107 offset:8064
	s_waitcnt lgkmcnt(7)
	global_store_dwordx4 v[28:29], v[2:5], off
	s_waitcnt lgkmcnt(6)
	global_store_dwordx4 v[78:79], v[6:9], off
	s_waitcnt lgkmcnt(5)
	global_store_dwordx4 v[80:81], v[10:13], off
	s_waitcnt lgkmcnt(4)
	global_store_dwordx4 v[82:83], v[30:33], off
	s_waitcnt lgkmcnt(3)
	global_store_dwordx4 v[84:85], v[34:37], off
	s_waitcnt lgkmcnt(2)
	global_store_dwordx4 v[86:87], v[38:41], off
	s_waitcnt lgkmcnt(1)
	global_store_dwordx4 v[50:51], v[42:45], off
	s_waitcnt lgkmcnt(0)
	global_store_dwordx4 v[52:53], v[46:49], off
	s_waitcnt lgkmcnt(0)
	global_load_dword v2, v[88:89], off
	global_load_dword v3, v[22:23], off
	v_mov_b32_e32 v4, 0
	v_mov_b32_e32 v6, 0
	s_waitcnt vmcnt(0)
	v_add_f32_e32 v2, v2, v3
	v_mul_f32_e32 v3, 0xbfb8aa3b, v2
	v_exp_f32_e32 v3, v3
	s_nop 0
	v_add_f32_e32 v3, 1.0, v3
	v_cmp_gt_f32_e32 vcc, s3, v3
	s_nop 1
	v_cndmask_b32_e64 v5, 0, 32, vcc
	v_ldexp_f32 v3, v3, v5
	v_log_f32_e32 v3, v3
	v_cndmask_b32_e32 v7, 0, v108, vcc
	v_mov_b32_e32 v5, 0
	v_mul_f32_e32 v8, 0x3f317217, v3
	v_fma_f32 v8, v3, s25, -v8
	v_fmac_f32_e32 v8, 0x3377d1cf, v3
	v_fmac_f32_e32 v8, 0x3f317217, v3
	v_cmp_lt_f32_e64 vcc, |v3|, s26
	s_nop 1
	v_cndmask_b32_e32 v3, v3, v8, vcc
	v_sub_f32_e32 v3, v3, v7
	v_cmp_gt_f32_e32 vcc, s24, v2
	s_nop 1
	v_cndmask_b32_e64 v2, v3, -v2, vcc
	v_mul_f32_e32 v3, 0xbfb8aa3b, v2
	s_nop 1
	v_mov_b32_dpp v4, v3 row_shr:1 row_mask:0xf bank_mask:0xf
	v_fmac_f32_e32 v4, 0xbfb8aa3b, v2
	s_nop 1
	v_add_f32_dpp v2, v4, v4 row_shr:2 row_mask:0xf bank_mask:0xf bound_ctrl:1
	s_nop 1
	v_add_f32_dpp v2, v2, v2 row_shr:4 row_mask:0xf bank_mask:0xf bound_ctrl:1
	s_nop 1
	v_add_f32_dpp v2, v2, v2 row_shr:8 row_mask:0xf bank_mask:0xf bound_ctrl:1
	s_nop 1
	v_mov_b32_dpp v5, v2 row_bcast:15 row_mask:0xa bank_mask:0xf
	v_add_f32_e32 v2, v2, v5
	v_lshl_add_u64 v[4:5], v[26:27], 2, v[24:25]
	s_nop 0
	v_mov_b32_dpp v6, v2 row_bcast:31 row_mask:0xc bank_mask:0xf
	v_add_f32_e32 v2, v2, v6
	global_store_dword v[4:5], v2, off
	s_and_saveexec_b64 s[14:15], s[8:9]
	s_cbranch_execz .LBB0_590
	v_add_u32_e32 v4, s27, v105
	v_ashrrev_i32_e32 v5, 31, v4
	v_readlane_b32 s30, v239, 3
	v_readlane_b32 s31, v239, 4
	s_nop 0
	v_lshl_add_u64 v[4:5], v[4:5], 2, s[30:31]
	global_store_dword v[4:5], v2, off
	s_branch .LBB0_590
